# ret_scan: 32-deep batched chunk loads (one latency per latent sequence instead of four) on top of mid-stage-barrier GEMM loops
# baseline (speedup 1.0000x reference)
.Lrsb_chk32:
	v_cmp_gt_u32_e64 s[0:1], 33, v3
	s_cmp_lg_u64 s[0:1], 0
	s_cbranch_scc1 .Lrsb_chk
	s_mov_b32 s0, 0xffff0000
	s_mov_b32 s1, -1
	v_mov_b64_e32 v[16:17], v[6:7]
	global_load_dword v32, v[16:17], off
	v_lshl_add_u64 v[16:17], v[16:17], 0, s[0:1]
	global_load_dword v33, v[16:17], off
	v_lshl_add_u64 v[16:17], v[16:17], 0, s[0:1]
	global_load_dword v34, v[16:17], off
	v_lshl_add_u64 v[16:17], v[16:17], 0, s[0:1]
	global_load_dword v35, v[16:17], off
	v_lshl_add_u64 v[16:17], v[16:17], 0, s[0:1]
	global_load_dword v36, v[16:17], off
	v_lshl_add_u64 v[16:17], v[16:17], 0, s[0:1]
	global_load_dword v37, v[16:17], off
	v_lshl_add_u64 v[16:17], v[16:17], 0, s[0:1]
	global_load_dword v38, v[16:17], off
	v_lshl_add_u64 v[16:17], v[16:17], 0, s[0:1]
	global_load_dword v39, v[16:17], off
	v_lshl_add_u64 v[16:17], v[16:17], 0, s[0:1]
	global_load_dword v40, v[16:17], off
	v_lshl_add_u64 v[16:17], v[16:17], 0, s[0:1]
	global_load_dword v41, v[16:17], off
	v_lshl_add_u64 v[16:17], v[16:17], 0, s[0:1]
	global_load_dword v42, v[16:17], off
	v_lshl_add_u64 v[16:17], v[16:17], 0, s[0:1]
	global_load_dword v43, v[16:17], off
	v_lshl_add_u64 v[16:17], v[16:17], 0, s[0:1]
	global_load_dword v44, v[16:17], off
	v_lshl_add_u64 v[16:17], v[16:17], 0, s[0:1]
	global_load_dword v45, v[16:17], off
	v_lshl_add_u64 v[16:17], v[16:17], 0, s[0:1]
	global_load_dword v46, v[16:17], off
	v_lshl_add_u64 v[16:17], v[16:17], 0, s[0:1]
	global_load_dword v47, v[16:17], off
	v_lshl_add_u64 v[16:17], v[16:17], 0, s[0:1]
	global_load_dword v48, v[16:17], off
	v_lshl_add_u64 v[16:17], v[16:17], 0, s[0:1]
	global_load_dword v49, v[16:17], off
	v_lshl_add_u64 v[16:17], v[16:17], 0, s[0:1]
	global_load_dword v50, v[16:17], off
	v_lshl_add_u64 v[16:17], v[16:17], 0, s[0:1]
	global_load_dword v51, v[16:17], off
	v_lshl_add_u64 v[16:17], v[16:17], 0, s[0:1]
	global_load_dword v52, v[16:17], off
	v_lshl_add_u64 v[16:17], v[16:17], 0, s[0:1]
	global_load_dword v53, v[16:17], off
	v_lshl_add_u64 v[16:17], v[16:17], 0, s[0:1]
	global_load_dword v54, v[16:17], off
	v_lshl_add_u64 v[16:17], v[16:17], 0, s[0:1]
	global_load_dword v55, v[16:17], off
	v_lshl_add_u64 v[16:17], v[16:17], 0, s[0:1]
	global_load_dword v56, v[16:17], off
	v_lshl_add_u64 v[16:17], v[16:17], 0, s[0:1]
	global_load_dword v57, v[16:17], off
	v_lshl_add_u64 v[16:17], v[16:17], 0, s[0:1]
	global_load_dword v58, v[16:17], off
	v_lshl_add_u64 v[16:17], v[16:17], 0, s[0:1]
	global_load_dword v59, v[16:17], off
	v_lshl_add_u64 v[16:17], v[16:17], 0, s[0:1]
	global_load_dword v60, v[16:17], off
	v_lshl_add_u64 v[16:17], v[16:17], 0, s[0:1]
	global_load_dword v61, v[16:17], off
	v_lshl_add_u64 v[16:17], v[16:17], 0, s[0:1]
	global_load_dword v62, v[16:17], off
	v_lshl_add_u64 v[16:17], v[16:17], 0, s[0:1]
	global_load_dword v63, v[16:17], off
	s_waitcnt vmcnt(31)
	global_store_dword v[6:7], v13, off
	v_fma_f32 v13, v1, v13, v32
	v_lshl_add_u64 v[6:7], v[6:7], 0, s[0:1]
	s_waitcnt vmcnt(31)
	global_store_dword v[6:7], v13, off
	v_fma_f32 v13, v1, v13, v33
	v_lshl_add_u64 v[6:7], v[6:7], 0, s[0:1]
	s_waitcnt vmcnt(31)
	global_store_dword v[6:7], v13, off
	v_fma_f32 v13, v1, v13, v34
	v_lshl_add_u64 v[6:7], v[6:7], 0, s[0:1]
	s_waitcnt vmcnt(31)
	global_store_dword v[6:7], v13, off
	v_fma_f32 v13, v1, v13, v35
	v_lshl_add_u64 v[6:7], v[6:7], 0, s[0:1]
	s_waitcnt vmcnt(31)
	global_store_dword v[6:7], v13, off
	v_fma_f32 v13, v1, v13, v36
	v_lshl_add_u64 v[6:7], v[6:7], 0, s[0:1]
	s_waitcnt vmcnt(31)
	global_store_dword v[6:7], v13, off
	v_fma_f32 v13, v1, v13, v37
	v_lshl_add_u64 v[6:7], v[6:7], 0, s[0:1]
	s_waitcnt vmcnt(31)
	global_store_dword v[6:7], v13, off
	v_fma_f32 v13, v1, v13, v38
	v_lshl_add_u64 v[6:7], v[6:7], 0, s[0:1]
	s_waitcnt vmcnt(31)
	global_store_dword v[6:7], v13, off
	v_fma_f32 v13, v1, v13, v39
	v_lshl_add_u64 v[6:7], v[6:7], 0, s[0:1]
	s_waitcnt vmcnt(31)
	global_store_dword v[6:7], v13, off
	v_fma_f32 v13, v1, v13, v40
	v_lshl_add_u64 v[6:7], v[6:7], 0, s[0:1]
	s_waitcnt vmcnt(31)
	global_store_dword v[6:7], v13, off
	v_fma_f32 v13, v1, v13, v41
	v_lshl_add_u64 v[6:7], v[6:7], 0, s[0:1]
	s_waitcnt vmcnt(31)
	global_store_dword v[6:7], v13, off
	v_fma_f32 v13, v1, v13, v42
	v_lshl_add_u64 v[6:7], v[6:7], 0, s[0:1]
	s_waitcnt vmcnt(31)
	global_store_dword v[6:7], v13, off
	v_fma_f32 v13, v1, v13, v43
	v_lshl_add_u64 v[6:7], v[6:7], 0, s[0:1]
	s_waitcnt vmcnt(31)
	global_store_dword v[6:7], v13, off
	v_fma_f32 v13, v1, v13, v44
	v_lshl_add_u64 v[6:7], v[6:7], 0, s[0:1]
	s_waitcnt vmcnt(31)
	global_store_dword v[6:7], v13, off
	v_fma_f32 v13, v1, v13, v45
	v_lshl_add_u64 v[6:7], v[6:7], 0, s[0:1]
	s_waitcnt vmcnt(31)
	global_store_dword v[6:7], v13, off
	v_fma_f32 v13, v1, v13, v46
	v_lshl_add_u64 v[6:7], v[6:7], 0, s[0:1]
	s_waitcnt vmcnt(31)
	global_store_dword v[6:7], v13, off
	v_fma_f32 v13, v1, v13, v47
	v_lshl_add_u64 v[6:7], v[6:7], 0, s[0:1]
	s_waitcnt vmcnt(31)
	global_store_dword v[6:7], v13, off
	v_fma_f32 v13, v1, v13, v48
	v_lshl_add_u64 v[6:7], v[6:7], 0, s[0:1]
	s_waitcnt vmcnt(31)
	global_store_dword v[6:7], v13, off
	v_fma_f32 v13, v1, v13, v49
	v_lshl_add_u64 v[6:7], v[6:7], 0, s[0:1]
	s_waitcnt vmcnt(31)
	global_store_dword v[6:7], v13, off
	v_fma_f32 v13, v1, v13, v50
	v_lshl_add_u64 v[6:7], v[6:7], 0, s[0:1]
	s_waitcnt vmcnt(31)
	global_store_dword v[6:7], v13, off
	v_fma_f32 v13, v1, v13, v51
	v_lshl_add_u64 v[6:7], v[6:7], 0, s[0:1]
	s_waitcnt vmcnt(31)
	global_store_dword v[6:7], v13, off
	v_fma_f32 v13, v1, v13, v52
	v_lshl_add_u64 v[6:7], v[6:7], 0, s[0:1]
	s_waitcnt vmcnt(31)
	global_store_dword v[6:7], v13, off
	v_fma_f32 v13, v1, v13, v53
	v_lshl_add_u64 v[6:7], v[6:7], 0, s[0:1]
	s_waitcnt vmcnt(31)
	global_store_dword v[6:7], v13, off
	v_fma_f32 v13, v1, v13, v54
	v_lshl_add_u64 v[6:7], v[6:7], 0, s[0:1]
	s_waitcnt vmcnt(31)
	global_store_dword v[6:7], v13, off
	v_fma_f32 v13, v1, v13, v55
	v_lshl_add_u64 v[6:7], v[6:7], 0, s[0:1]
	s_waitcnt vmcnt(31)
	global_store_dword v[6:7], v13, off
	v_fma_f32 v13, v1, v13, v56
	v_lshl_add_u64 v[6:7], v[6:7], 0, s[0:1]
	s_waitcnt vmcnt(31)
	global_store_dword v[6:7], v13, off
	v_fma_f32 v13, v1, v13, v57
	v_lshl_add_u64 v[6:7], v[6:7], 0, s[0:1]
	s_waitcnt vmcnt(31)
	global_store_dword v[6:7], v13, off
	v_fma_f32 v13, v1, v13, v58
	v_lshl_add_u64 v[6:7], v[6:7], 0, s[0:1]
	s_waitcnt vmcnt(31)
	global_store_dword v[6:7], v13, off
	v_fma_f32 v13, v1, v13, v59
	v_lshl_add_u64 v[6:7], v[6:7], 0, s[0:1]
	s_waitcnt vmcnt(31)
	global_store_dword v[6:7], v13, off
	v_fma_f32 v13, v1, v13, v60
	v_lshl_add_u64 v[6:7], v[6:7], 0, s[0:1]
	s_waitcnt vmcnt(31)
	global_store_dword v[6:7], v13, off
	v_fma_f32 v13, v1, v13, v61
	v_lshl_add_u64 v[6:7], v[6:7], 0, s[0:1]
	s_waitcnt vmcnt(31)
	global_store_dword v[6:7], v13, off
	v_fma_f32 v13, v1, v13, v62
	v_lshl_add_u64 v[6:7], v[6:7], 0, s[0:1]
	s_waitcnt vmcnt(31)
	global_store_dword v[6:7], v13, off
	v_fma_f32 v13, v1, v13, v63
	v_lshl_add_u64 v[6:7], v[6:7], 0, s[0:1]
	v_subrev_u32_e32 v3, 32, v3
	v_cmp_ne_u32_e64 s[0:1], 1, v3
	s_cmp_lg_u64 s[0:1], 0
	s_cbranch_scc1 .Lrsb_chk32
	s_branch .Lrsb_done

.Lrsf_chk32:
	v_cmp_gt_u32_e64 s[0:1], 32, v11
	s_cmp_lg_u64 s[0:1], 0
	s_cbranch_scc1 .Lrsf_chk
	s_mov_b64 s[0:1], 0x10000
	v_mov_b64_e32 v[16:17], v[6:7]
	global_load_dword v32, v[16:17], off
	v_lshl_add_u64 v[16:17], v[16:17], 0, s[0:1]
	global_load_dword v33, v[16:17], off
	v_lshl_add_u64 v[16:17], v[16:17], 0, s[0:1]
	global_load_dword v34, v[16:17], off
	v_lshl_add_u64 v[16:17], v[16:17], 0, s[0:1]
	global_load_dword v35, v[16:17], off
	v_lshl_add_u64 v[16:17], v[16:17], 0, s[0:1]
	global_load_dword v36, v[16:17], off
	v_lshl_add_u64 v[16:17], v[16:17], 0, s[0:1]
	global_load_dword v37, v[16:17], off
	v_lshl_add_u64 v[16:17], v[16:17], 0, s[0:1]
	global_load_dword v38, v[16:17], off
	v_lshl_add_u64 v[16:17], v[16:17], 0, s[0:1]
	global_load_dword v39, v[16:17], off
	v_lshl_add_u64 v[16:17], v[16:17], 0, s[0:1]
	global_load_dword v40, v[16:17], off
	v_lshl_add_u64 v[16:17], v[16:17], 0, s[0:1]
	global_load_dword v41, v[16:17], off
	v_lshl_add_u64 v[16:17], v[16:17], 0, s[0:1]
	global_load_dword v42, v[16:17], off
	v_lshl_add_u64 v[16:17], v[16:17], 0, s[0:1]
	global_load_dword v43, v[16:17], off
	v_lshl_add_u64 v[16:17], v[16:17], 0, s[0:1]
	global_load_dword v44, v[16:17], off
	v_lshl_add_u64 v[16:17], v[16:17], 0, s[0:1]
	global_load_dword v45, v[16:17], off
	v_lshl_add_u64 v[16:17], v[16:17], 0, s[0:1]
	global_load_dword v46, v[16:17], off
	v_lshl_add_u64 v[16:17], v[16:17], 0, s[0:1]
	global_load_dword v47, v[16:17], off
	v_lshl_add_u64 v[16:17], v[16:17], 0, s[0:1]
	global_load_dword v48, v[16:17], off
	v_lshl_add_u64 v[16:17], v[16:17], 0, s[0:1]
	global_load_dword v49, v[16:17], off
	v_lshl_add_u64 v[16:17], v[16:17], 0, s[0:1]
	global_load_dword v50, v[16:17], off
	v_lshl_add_u64 v[16:17], v[16:17], 0, s[0:1]
	global_load_dword v51, v[16:17], off
	v_lshl_add_u64 v[16:17], v[16:17], 0, s[0:1]
	global_load_dword v52, v[16:17], off
	v_lshl_add_u64 v[16:17], v[16:17], 0, s[0:1]
	global_load_dword v53, v[16:17], off
	v_lshl_add_u64 v[16:17], v[16:17], 0, s[0:1]
	global_load_dword v54, v[16:17], off
	v_lshl_add_u64 v[16:17], v[16:17], 0, s[0:1]
	global_load_dword v55, v[16:17], off
	v_lshl_add_u64 v[16:17], v[16:17], 0, s[0:1]
	global_load_dword v56, v[16:17], off
	v_lshl_add_u64 v[16:17], v[16:17], 0, s[0:1]
	global_load_dword v57, v[16:17], off
	v_lshl_add_u64 v[16:17], v[16:17], 0, s[0:1]
	global_load_dword v58, v[16:17], off
	v_lshl_add_u64 v[16:17], v[16:17], 0, s[0:1]
	global_load_dword v59, v[16:17], off
	v_lshl_add_u64 v[16:17], v[16:17], 0, s[0:1]
	global_load_dword v60, v[16:17], off
	v_lshl_add_u64 v[16:17], v[16:17], 0, s[0:1]
	global_load_dword v61, v[16:17], off
	v_lshl_add_u64 v[16:17], v[16:17], 0, s[0:1]
	global_load_dword v62, v[16:17], off
	v_lshl_add_u64 v[16:17], v[16:17], 0, s[0:1]
	global_load_dword v63, v[16:17], off
	s_waitcnt vmcnt(31)
	global_store_dword v[6:7], v13, off
	v_fma_f32 v13, v1, v13, v32
	v_lshl_add_u64 v[6:7], v[6:7], 0, s[0:1]
	s_waitcnt vmcnt(31)
	global_store_dword v[6:7], v13, off
	v_fma_f32 v13, v1, v13, v33
	v_lshl_add_u64 v[6:7], v[6:7], 0, s[0:1]
	s_waitcnt vmcnt(31)
	global_store_dword v[6:7], v13, off
	v_fma_f32 v13, v1, v13, v34
	v_lshl_add_u64 v[6:7], v[6:7], 0, s[0:1]
	s_waitcnt vmcnt(31)
	global_store_dword v[6:7], v13, off
	v_fma_f32 v13, v1, v13, v35
	v_lshl_add_u64 v[6:7], v[6:7], 0, s[0:1]
	s_waitcnt vmcnt(31)
	global_store_dword v[6:7], v13, off
	v_fma_f32 v13, v1, v13, v36
	v_lshl_add_u64 v[6:7], v[6:7], 0, s[0:1]
	s_waitcnt vmcnt(31)
	global_store_dword v[6:7], v13, off
	v_fma_f32 v13, v1, v13, v37
	v_lshl_add_u64 v[6:7], v[6:7], 0, s[0:1]
	s_waitcnt vmcnt(31)
	global_store_dword v[6:7], v13, off
	v_fma_f32 v13, v1, v13, v38
	v_lshl_add_u64 v[6:7], v[6:7], 0, s[0:1]
	s_waitcnt vmcnt(31)
	global_store_dword v[6:7], v13, off
	v_fma_f32 v13, v1, v13, v39
	v_lshl_add_u64 v[6:7], v[6:7], 0, s[0:1]
	s_waitcnt vmcnt(31)
	global_store_dword v[6:7], v13, off
	v_fma_f32 v13, v1, v13, v40
	v_lshl_add_u64 v[6:7], v[6:7], 0, s[0:1]
	s_waitcnt vmcnt(31)
	global_store_dword v[6:7], v13, off
	v_fma_f32 v13, v1, v13, v41
	v_lshl_add_u64 v[6:7], v[6:7], 0, s[0:1]
	s_waitcnt vmcnt(31)
	global_store_dword v[6:7], v13, off
	v_fma_f32 v13, v1, v13, v42
	v_lshl_add_u64 v[6:7], v[6:7], 0, s[0:1]
	s_waitcnt vmcnt(31)
	global_store_dword v[6:7], v13, off
	v_fma_f32 v13, v1, v13, v43
	v_lshl_add_u64 v[6:7], v[6:7], 0, s[0:1]
	s_waitcnt vmcnt(31)
	global_store_dword v[6:7], v13, off
	v_fma_f32 v13, v1, v13, v44
	v_lshl_add_u64 v[6:7], v[6:7], 0, s[0:1]
	s_waitcnt vmcnt(31)
	global_store_dword v[6:7], v13, off
	v_fma_f32 v13, v1, v13, v45
	v_lshl_add_u64 v[6:7], v[6:7], 0, s[0:1]
	s_waitcnt vmcnt(31)
	global_store_dword v[6:7], v13, off
	v_fma_f32 v13, v1, v13, v46
	v_lshl_add_u64 v[6:7], v[6:7], 0, s[0:1]
	s_waitcnt vmcnt(31)
	global_store_dword v[6:7], v13, off
	v_fma_f32 v13, v1, v13, v47
	v_lshl_add_u64 v[6:7], v[6:7], 0, s[0:1]
	s_waitcnt vmcnt(31)
	global_store_dword v[6:7], v13, off
	v_fma_f32 v13, v1, v13, v48
	v_lshl_add_u64 v[6:7], v[6:7], 0, s[0:1]
	s_waitcnt vmcnt(31)
	global_store_dword v[6:7], v13, off
	v_fma_f32 v13, v1, v13, v49
	v_lshl_add_u64 v[6:7], v[6:7], 0, s[0:1]
	s_waitcnt vmcnt(31)
	global_store_dword v[6:7], v13, off
	v_fma_f32 v13, v1, v13, v50
	v_lshl_add_u64 v[6:7], v[6:7], 0, s[0:1]
	s_waitcnt vmcnt(31)
	global_store_dword v[6:7], v13, off
	v_fma_f32 v13, v1, v13, v51
	v_lshl_add_u64 v[6:7], v[6:7], 0, s[0:1]
	s_waitcnt vmcnt(31)
	global_store_dword v[6:7], v13, off
	v_fma_f32 v13, v1, v13, v52
	v_lshl_add_u64 v[6:7], v[6:7], 0, s[0:1]
	s_waitcnt vmcnt(31)
	global_store_dword v[6:7], v13, off
	v_fma_f32 v13, v1, v13, v53
	v_lshl_add_u64 v[6:7], v[6:7], 0, s[0:1]
	s_waitcnt vmcnt(31)
	global_store_dword v[6:7], v13, off
	v_fma_f32 v13, v1, v13, v54
	v_lshl_add_u64 v[6:7], v[6:7], 0, s[0:1]
	s_waitcnt vmcnt(31)
	global_store_dword v[6:7], v13, off
	v_fma_f32 v13, v1, v13, v55
	v_lshl_add_u64 v[6:7], v[6:7], 0, s[0:1]
	s_waitcnt vmcnt(31)
	global_store_dword v[6:7], v13, off
	v_fma_f32 v13, v1, v13, v56
	v_lshl_add_u64 v[6:7], v[6:7], 0, s[0:1]
	s_waitcnt vmcnt(31)
	global_store_dword v[6:7], v13, off
	v_fma_f32 v13, v1, v13, v57
	v_lshl_add_u64 v[6:7], v[6:7], 0, s[0:1]
	s_waitcnt vmcnt(31)
	global_store_dword v[6:7], v13, off
	v_fma_f32 v13, v1, v13, v58
	v_lshl_add_u64 v[6:7], v[6:7], 0, s[0:1]
	s_waitcnt vmcnt(31)
	global_store_dword v[6:7], v13, off
	v_fma_f32 v13, v1, v13, v59
	v_lshl_add_u64 v[6:7], v[6:7], 0, s[0:1]
	s_waitcnt vmcnt(31)
	global_store_dword v[6:7], v13, off
	v_fma_f32 v13, v1, v13, v60
	v_lshl_add_u64 v[6:7], v[6:7], 0, s[0:1]
	s_waitcnt vmcnt(31)
	global_store_dword v[6:7], v13, off
	v_fma_f32 v13, v1, v13, v61
	v_lshl_add_u64 v[6:7], v[6:7], 0, s[0:1]
	s_waitcnt vmcnt(31)
	global_store_dword v[6:7], v13, off
	v_fma_f32 v13, v1, v13, v62
	v_lshl_add_u64 v[6:7], v[6:7], 0, s[0:1]
	s_waitcnt vmcnt(31)
	global_store_dword v[6:7], v13, off
	v_fma_f32 v13, v1, v13, v63
	v_lshl_add_u64 v[6:7], v[6:7], 0, s[0:1]
	v_subrev_u32_e32 v11, 32, v11
	v_cmp_ne_u32_e64 s[0:1], 0, v11
	s_cmp_lg_u64 s[0:1], 0
	s_cbranch_scc1 .Lrsf_chk32
	s_branch .Lrsf_done
